# diff_attn: stale K/V DMA drain moved off the unit finalisation (next unit's prologue still drains before reusing the ring)
# baseline (speedup 1.0000x reference)
.Ldf_nodrain:
	s_and_saveexec_b64 s[6:7], s[0:1]
	s_xor_b64 s[0:1], exec, s[6:7]
	s_cbranch_execz .LBB0_1582
	v_div_scale_f32 v0, s[6:7], v88, v88, 1.0
	v_rcp_f32_e32 v2, v0
	v_div_scale_f32 v3, vcc, 1.0, v88, 1.0
	v_readlane_b32 s36, v255, 2
	v_fma_f32 v4, -v0, v2, 1.0
	v_fmac_f32_e32 v2, v4, v2
	v_mul_f32_e32 v4, v3, v2
	v_fma_f32 v5, -v0, v4, v3
	v_fmac_f32_e32 v4, v5, v2
	v_fma_f32 v0, -v0, v4, v3
	v_div_scale_f32 v3, s[6:7], v76, v76, v141
	v_rcp_f32_e32 v5, v3
	v_div_fmas_f32 v0, v0, v2, v4
	v_div_fixup_f32 v0, v0, v88, 1.0
	v_readlane_b32 s50, v255, 16
	v_fma_f32 v2, -v3, v5, 1.0
	v_fmac_f32_e32 v5, v2, v5
	v_div_scale_f32 v2, vcc, v141, v76, v141
	v_mul_f32_e32 v4, v2, v5
	v_fma_f32 v6, -v3, v4, v2
	v_fmac_f32_e32 v4, v6, v5
	v_fma_f32 v2, -v3, v4, v2
	v_div_fmas_f32 v2, v2, v5, v4
	v_div_fixup_f32 v6, v2, v76, v141
	v_pk_mul_f32 v[2:3], v[80:81], v[6:7] op_sel_hi:[1,0]
	v_readlane_b32 s51, v255, 17
	v_pk_fma_f32 v[8:9], v[84:85], v[0:1], v[2:3] op_sel_hi:[1,0,1] neg_lo:[0,0,1] neg_hi:[0,0,1]
	v_pk_mul_f32 v[2:3], v[82:83], v[6:7] op_sel_hi:[1,0]
	v_pk_mul_f32 v[66:67], v[66:67], v[6:7] op_sel_hi:[1,0]
	v_pk_fma_f32 v[12:13], v[86:87], v[0:1], v[2:3] op_sel_hi:[1,0,1] neg_lo:[0,0,1] neg_hi:[0,0,1]
	v_pk_mul_f32 v[2:3], v[74:75], v[6:7] op_sel_hi:[1,0]
	v_pk_mul_f32 v[64:65], v[64:65], v[6:7] op_sel_hi:[1,0]
	v_pk_fma_f32 v[16:17], v[70:71], v[0:1], v[2:3] op_sel_hi:[1,0,1] neg_lo:[0,0,1] neg_hi:[0,0,1]
	global_load_dwordx4 v[182:185], v108, s[50:51]
	global_load_dwordx4 v[186:189], v108, s[50:51] offset:64
	global_load_dwordx4 v[190:193], v108, s[50:51] offset:128
	global_load_dwordx4 v[194:197], v108, s[50:51] offset:192
	global_load_dwordx4 v[198:201], v108, s[50:51] offset:256
	global_load_dwordx4 v[202:205], v108, s[50:51] offset:320
	global_load_dwordx4 v[206:209], v108, s[50:51] offset:384
	global_load_dwordx4 v[210:213], v108, s[50:51] offset:448
	v_pk_mul_f32 v[70:71], v[72:73], v[6:7] op_sel_hi:[1,0]
	v_pk_mul_f32 v[58:59], v[58:59], v[6:7] op_sel_hi:[1,0]
	v_pk_fma_f32 v[68:69], v[68:69], v[0:1], v[70:71] op_sel_hi:[1,0,1] neg_lo:[0,0,1] neg_hi:[0,0,1]
	v_pk_mul_f32 v[56:57], v[56:57], v[6:7] op_sel_hi:[1,0]
	v_pk_mul_f32 v[70:71], v[68:69], v[68:69]
	v_pk_mul_f32 v[50:51], v[50:51], v[6:7] op_sel_hi:[1,0]
	v_pk_mul_f32 v[48:49], v[48:49], v[6:7] op_sel_hi:[1,0]
	v_pk_mul_f32 v[42:43], v[42:43], v[6:7] op_sel_hi:[1,0]
	v_pk_mul_f32 v[40:41], v[40:41], v[6:7] op_sel_hi:[1,0]
	v_pk_mul_f32 v[30:31], v[30:31], v[6:7] op_sel_hi:[1,0]
	v_pk_mul_f32 v[28:29], v[28:29], v[6:7] op_sel_hi:[1,0]
	v_pk_mul_f32 v[22:23], v[22:23], v[6:7] op_sel_hi:[1,0]
	v_pk_mul_f32 v[6:7], v[20:21], v[6:7] op_sel_hi:[1,0]
	v_pk_mul_f32 v[18:19], v[16:17], v[16:17]
	v_pk_fma_f32 v[62:63], v[62:63], v[0:1], v[66:67] op_sel_hi:[1,0,1] neg_lo:[0,0,1] neg_hi:[0,0,1]
	v_pk_fma_f32 v[60:61], v[60:61], v[0:1], v[64:65] op_sel_hi:[1,0,1] neg_lo:[0,0,1] neg_hi:[0,0,1]
	v_pk_fma_f32 v[54:55], v[54:55], v[0:1], v[58:59] op_sel_hi:[1,0,1] neg_lo:[0,0,1] neg_hi:[0,0,1]
	v_pk_fma_f32 v[52:53], v[52:53], v[0:1], v[56:57] op_sel_hi:[1,0,1] neg_lo:[0,0,1] neg_hi:[0,0,1]
	v_pk_fma_f32 v[46:47], v[46:47], v[0:1], v[50:51] op_sel_hi:[1,0,1] neg_lo:[0,0,1] neg_hi:[0,0,1]
	v_pk_fma_f32 v[44:45], v[44:45], v[0:1], v[48:49] op_sel_hi:[1,0,1] neg_lo:[0,0,1] neg_hi:[0,0,1]
	v_pk_fma_f32 v[38:39], v[38:39], v[0:1], v[42:43] op_sel_hi:[1,0,1] neg_lo:[0,0,1] neg_hi:[0,0,1]
	v_pk_fma_f32 v[36:37], v[36:37], v[0:1], v[40:41] op_sel_hi:[1,0,1] neg_lo:[0,0,1] neg_hi:[0,0,1]
	v_pk_fma_f32 v[30:31], v[34:35], v[0:1], v[30:31] op_sel_hi:[1,0,1] neg_lo:[0,0,1] neg_hi:[0,0,1]
	v_pk_fma_f32 v[28:29], v[32:33], v[0:1], v[28:29] op_sel_hi:[1,0,1] neg_lo:[0,0,1] neg_hi:[0,0,1]
	v_pk_fma_f32 v[22:23], v[26:27], v[0:1], v[22:23] op_sel_hi:[1,0,1] neg_lo:[0,0,1] neg_hi:[0,0,1]
	v_pk_fma_f32 v[6:7], v[24:25], v[0:1], v[6:7] op_sel_hi:[1,0,1] neg_lo:[0,0,1] neg_hi:[0,0,1]
	v_add_f32_e32 v0, v70, v71
	v_add_f32_e32 v0, v18, v0
	v_pk_mul_f32 v[64:65], v[60:61], v[60:61]
	v_add_f32_e32 v0, v19, v0
	v_add_f32_e32 v0, v64, v0
	v_pk_mul_f32 v[66:67], v[62:63], v[62:63]
	v_add_f32_e32 v0, v65, v0
	v_add_f32_e32 v0, v66, v0
	v_pk_mul_f32 v[56:57], v[52:53], v[52:53]
	v_add_f32_e32 v0, v67, v0
	v_add_f32_e32 v0, v56, v0
	v_pk_mul_f32 v[58:59], v[54:55], v[54:55]
	v_add_f32_e32 v0, v57, v0
	v_add_f32_e32 v0, v58, v0
	v_pk_mul_f32 v[48:49], v[44:45], v[44:45]
	v_add_f32_e32 v0, v59, v0
	v_add_f32_e32 v0, v48, v0
	v_pk_mul_f32 v[50:51], v[46:47], v[46:47]
	v_add_f32_e32 v0, v49, v0
	v_add_f32_e32 v0, v50, v0
	v_pk_mul_f32 v[40:41], v[36:37], v[36:37]
	v_add_f32_e32 v0, v51, v0
	v_add_f32_e32 v0, v40, v0
	v_pk_mul_f32 v[42:43], v[38:39], v[38:39]
	v_add_f32_e32 v0, v41, v0
	v_add_f32_e32 v0, v42, v0
	v_pk_mul_f32 v[32:33], v[28:29], v[28:29]
	v_add_f32_e32 v0, v43, v0
	v_add_f32_e32 v0, v32, v0
	v_pk_mul_f32 v[34:35], v[30:31], v[30:31]
	v_add_f32_e32 v0, v33, v0
	v_add_f32_e32 v0, v34, v0
	v_pk_mul_f32 v[20:21], v[6:7], v[6:7]
	v_add_f32_e32 v0, v35, v0
	v_add_f32_e32 v0, v20, v0
	v_pk_mul_f32 v[26:27], v[22:23], v[22:23]
	v_add_f32_e32 v0, v21, v0
	v_add_f32_e32 v0, v26, v0
	v_pk_mul_f32 v[10:11], v[8:9], v[8:9]
	v_add_f32_e32 v0, v27, v0
	v_add_f32_e32 v0, v10, v0
	v_pk_mul_f32 v[14:15], v[12:13], v[12:13]
	v_add_f32_e32 v0, v11, v0
	v_add_f32_e32 v0, v14, v0
	v_add_f32_e32 v0, v15, v0
	ds_bpermute_b32 v10, v146, v0
	v_readlane_b32 s37, v255, 3
	v_readlane_b32 s36, v255, 18
	v_readlane_b32 s37, v255, 19
	v_readlane_b32 s38, v255, 4
	s_waitcnt lgkmcnt(0)
	v_add_f32_e32 v0, v0, v10
	ds_bpermute_b32 v14, v147, v0
	v_lshl_add_u64 v[10:11], s[26:27], 0, v[110:111]
	v_lshl_add_u64 v[10:11], s[76:77], 1, v[10:11]
	v_readlane_b32 s39, v255, 5
	v_readlane_b32 s40, v255, 6
	s_waitcnt lgkmcnt(0)
	v_add_f32_e32 v0, v0, v14
	v_fmamk_f32 v0, v0, 0x3c000000, v142
	v_mul_f32_e32 v14, 0x4b800000, v0
	v_cmp_gt_f32_e32 vcc, s71, v0
	v_readlane_b32 s41, v255, 7
	v_readlane_b32 s42, v255, 8
	v_cndmask_b32_e32 v0, v0, v14, vcc
	v_rsq_f32_e32 v14, v0
	v_lshlrev_b32_e32 v0, 3, v145
	v_lshl_add_u64 v[10:11], v[10:11], 0, v[0:1]
	v_readlane_b32 s43, v255, 9
	v_mul_f32_e32 v0, 0x45800000, v14
	v_cndmask_b32_e32 v0, v14, v0, vcc
	v_mul_f32_e32 v0, 0x3f24fd5c, v0
	v_readlane_b32 s44, v255, 10
	v_readlane_b32 s45, v255, 11
	v_readlane_b32 s46, v255, 12
	v_readlane_b32 s47, v255, 13
	v_readlane_b32 s48, v255, 14
	v_readlane_b32 s49, v255, 15
	s_waitcnt vmcnt(0)
	v_pk_mul_f32 v[14:15], v[68:69], v[0:1] op_sel_hi:[1,0]
	v_pk_mul_f32 v[16:17], v[16:17], v[0:1] op_sel_hi:[1,0]
	v_pk_mul_f32 v[14:15], v[14:15], v[182:183]
	v_pk_mul_f32 v[16:17], v[16:17], v[184:185]
	v_cvt_pk_bf16_f32 v92, v14, v15
	v_cvt_pk_bf16_f32 v93, v16, v17
	global_store_dwordx2 v[10:11], v[92:93], off
	v_pk_mul_f32 v[14:15], v[60:61], v[0:1] op_sel_hi:[1,0]
	v_pk_mul_f32 v[16:17], v[62:63], v[0:1] op_sel_hi:[1,0]
	v_pk_mul_f32 v[14:15], v[14:15], v[186:187]
	v_pk_mul_f32 v[16:17], v[16:17], v[188:189]
	v_cvt_pk_bf16_f32 v94, v14, v15
	v_cvt_pk_bf16_f32 v95, v16, v17
	global_store_dwordx2 v[10:11], v[94:95], off offset:32
	v_pk_mul_f32 v[14:15], v[52:53], v[0:1] op_sel_hi:[1,0]
	v_pk_mul_f32 v[16:17], v[54:55], v[0:1] op_sel_hi:[1,0]
	v_pk_mul_f32 v[14:15], v[14:15], v[190:191]
	v_pk_mul_f32 v[16:17], v[16:17], v[192:193]
	v_cvt_pk_bf16_f32 v96, v14, v15
	v_cvt_pk_bf16_f32 v97, v16, v17
	global_store_dwordx2 v[10:11], v[96:97], off offset:64
	v_pk_mul_f32 v[14:15], v[44:45], v[0:1] op_sel_hi:[1,0]
	v_pk_mul_f32 v[16:17], v[46:47], v[0:1] op_sel_hi:[1,0]
	v_pk_mul_f32 v[14:15], v[14:15], v[194:195]
	v_pk_mul_f32 v[16:17], v[16:17], v[196:197]
	v_cvt_pk_bf16_f32 v98, v14, v15
	v_cvt_pk_bf16_f32 v99, v16, v17
	global_store_dwordx2 v[10:11], v[98:99], off offset:96
	v_pk_mul_f32 v[14:15], v[36:37], v[0:1] op_sel_hi:[1,0]
	v_pk_mul_f32 v[16:17], v[38:39], v[0:1] op_sel_hi:[1,0]
	v_pk_mul_f32 v[14:15], v[14:15], v[198:199]
	v_pk_mul_f32 v[16:17], v[16:17], v[200:201]
	v_cvt_pk_bf16_f32 v100, v14, v15
	v_cvt_pk_bf16_f32 v101, v16, v17
	global_store_dwordx2 v[10:11], v[100:101], off offset:128
	v_pk_mul_f32 v[14:15], v[28:29], v[0:1] op_sel_hi:[1,0]
	v_pk_mul_f32 v[16:17], v[30:31], v[0:1] op_sel_hi:[1,0]
	v_pk_mul_f32 v[14:15], v[14:15], v[202:203]
	v_pk_mul_f32 v[16:17], v[16:17], v[204:205]
	v_cvt_pk_bf16_f32 v102, v14, v15
	v_cvt_pk_bf16_f32 v103, v16, v17
	global_store_dwordx2 v[10:11], v[102:103], off offset:160
	v_pk_mul_f32 v[14:15], v[6:7], v[0:1] op_sel_hi:[1,0]
	v_pk_mul_f32 v[16:17], v[22:23], v[0:1] op_sel_hi:[1,0]
	v_pk_mul_f32 v[14:15], v[14:15], v[206:207]
	v_pk_mul_f32 v[16:17], v[16:17], v[208:209]
	v_cvt_pk_bf16_f32 v104, v14, v15
	v_cvt_pk_bf16_f32 v105, v16, v17
	global_store_dwordx2 v[10:11], v[104:105], off offset:192
	v_pk_mul_f32 v[14:15], v[8:9], v[0:1] op_sel_hi:[1,0]
	v_pk_mul_f32 v[16:17], v[12:13], v[0:1] op_sel_hi:[1,0]
	v_pk_mul_f32 v[14:15], v[14:15], v[210:211]
	v_pk_mul_f32 v[16:17], v[16:17], v[212:213]
	v_cvt_pk_bf16_f32 v106, v14, v15
	v_cvt_pk_bf16_f32 v107, v16, v17
	global_store_dwordx2 v[10:11], v[106:107], off offset:224
	s_branch .LBB0_1582
